# v13 with the weight-line touch issued before load segment 2's vmcnt wait instead of after it (waits 8/9/9/9)
# speedup vs baseline: 1.0198x; 1.0198x over previous
.LBB0_341:
	s_add_u32 s14, s12, 0xfff00080
	s_addc_u32 s15, s13, -1
	s_cmp_eq_u32 s39, 60
	s_cselect_b32 s17, s51, s15
	s_cselect_b32 s16, s50, s14
	s_cselect_b32 s15, s53, s1
	s_cselect_b32 s14, s52, s0
	s_add_i32 m0, s8, 0xc000
	ds_read_b128 v[152:155], v252
	ds_read_b128 v[162:165], v252 offset:1024
	global_load_lds_dwordx4 v148, s[12:13]
	s_add_i32 m0, s8, 0xe000
	ds_read_b128 v[166:169], v252 offset:2048
	ds_read_b128 v[170:173], v252 offset:3072
	global_load_lds_dwordx4 v150, s[12:13]
	ds_read_b128 v[174:177], v252 offset:16384
	ds_read_b128 v[182:185], v252 offset:17408
	ds_read_b128 v[186:189], v252 offset:18432
	ds_read_b128 v[190:193], v252 offset:19456
	ds_read_b128 v[194:197], v161
	ds_read_b128 v[198:201], v161 offset:1024
	ds_read_b128 v[202:205], v161 offset:2048
	ds_read_b128 v[206:209], v161 offset:3072
	ds_read_b128 v[210:213], v161 offset:4096
	ds_read_b128 v[214:217], v161 offset:5120
	ds_read_b128 v[218:221], v161 offset:6144
	ds_read_b128 v[222:225], v161 offset:7168
	s_waitcnt vmcnt(8)
	s_waitcnt lgkmcnt(0)
	s_barrier
	v_mfma_f32_16x16x32_bf16 v[126:129], v[152:155], v[194:197], v[126:129]
	v_mfma_f32_16x16x32_bf16 v[126:129], v[162:165], v[198:201], v[126:129]
	v_mfma_f32_16x16x32_bf16 v[122:125], v[166:169], v[194:197], v[122:125]
	v_mfma_f32_16x16x32_bf16 v[122:125], v[170:173], v[198:201], v[122:125]
	v_mfma_f32_16x16x32_bf16 v[110:113], v[152:155], v[202:205], v[110:113]
	v_mfma_f32_16x16x32_bf16 v[110:113], v[162:165], v[206:209], v[110:113]
	v_mfma_f32_16x16x32_bf16 v[106:109], v[166:169], v[202:205], v[106:109]
	v_mfma_f32_16x16x32_bf16 v[106:109], v[170:173], v[206:209], v[106:109]
	v_mfma_f32_16x16x32_bf16 v[94:97], v[152:155], v[210:213], v[94:97]
	v_mfma_f32_16x16x32_bf16 v[94:97], v[162:165], v[214:217], v[94:97]
	v_mfma_f32_16x16x32_bf16 v[90:93], v[166:169], v[210:213], v[90:93]
	v_mfma_f32_16x16x32_bf16 v[90:93], v[170:173], v[214:217], v[90:93]
	v_mfma_f32_16x16x32_bf16 v[78:81], v[152:155], v[218:221], v[78:81]
	v_mfma_f32_16x16x32_bf16 v[78:81], v[162:165], v[222:225], v[78:81]
	v_mfma_f32_16x16x32_bf16 v[74:77], v[166:169], v[218:221], v[74:77]
	v_mfma_f32_16x16x32_bf16 v[74:77], v[170:173], v[222:225], v[74:77]
	v_mfma_f32_16x16x32_bf16 v[118:121], v[174:177], v[194:197], v[118:121]
	v_mfma_f32_16x16x32_bf16 v[118:121], v[182:185], v[198:201], v[118:121]
	v_mfma_f32_16x16x32_bf16 v[114:117], v[186:189], v[194:197], v[114:117]
	v_mfma_f32_16x16x32_bf16 v[114:117], v[190:193], v[198:201], v[114:117]
	v_mfma_f32_16x16x32_bf16 v[102:105], v[174:177], v[202:205], v[102:105]
	v_mfma_f32_16x16x32_bf16 v[102:105], v[182:185], v[206:209], v[102:105]
	v_mfma_f32_16x16x32_bf16 v[98:101], v[186:189], v[202:205], v[98:101]
	v_mfma_f32_16x16x32_bf16 v[98:101], v[190:193], v[206:209], v[98:101]
	v_mfma_f32_16x16x32_bf16 v[86:89], v[174:177], v[210:213], v[86:89]
	v_mfma_f32_16x16x32_bf16 v[86:89], v[182:185], v[214:217], v[86:89]
	v_mfma_f32_16x16x32_bf16 v[82:85], v[186:189], v[210:213], v[82:85]
	v_mfma_f32_16x16x32_bf16 v[82:85], v[190:193], v[214:217], v[82:85]
	v_mfma_f32_16x16x32_bf16 v[70:73], v[174:177], v[218:221], v[70:73]
	v_mfma_f32_16x16x32_bf16 v[70:73], v[182:185], v[222:225], v[70:73]
	v_mfma_f32_16x16x32_bf16 v[66:69], v[186:189], v[218:221], v[66:69]
	v_mfma_f32_16x16x32_bf16 v[66:69], v[190:193], v[222:225], v[66:69]
	s_barrier
	s_add_i32 m0, s28, 0x10000
	ds_read_b128 v[194:197], v161 offset:16384
	ds_read_b128 v[198:201], v161 offset:17408
	global_load_lds_dwordx4 v144, s[14:15]
	s_add_i32 m0, s28, 0x12000
	s_add_u32 s98, s14, 0x100000
	s_addc_u32 s99, s15, 0
	ds_read_b128 v[202:205], v161 offset:18432
	global_load_lds_dwordx4 v140, s[14:15]
	s_add_i32 m0, s28, 0x14000
	ds_read_b128 v[206:209], v161 offset:19456
	ds_read_b128 v[210:213], v161 offset:20480
	global_load_lds_dwordx4 v144, s[98:99]
	s_add_i32 m0, s28, 0x16000
	ds_read_b128 v[214:217], v161 offset:21504
	ds_read_b128 v[218:221], v161 offset:22528
	global_load_lds_dwordx4 v140, s[98:99]
	s_mov_b32 m0, s8
	ds_read_b128 v[222:225], v161 offset:23552
	global_load_lds_dwordx4 v146, s[16:17]
	s_mov_b32 m0, s9
	s_nop 0
	global_load_lds_dwordx4 v142, s[16:17]
	s_add_u32 s100, s14, 0x100
	s_addc_u32 s101, s15, 0
	s_cmp_eq_u32 s39, 58
	s_cselect_b32 s100, s52, s100
	s_cselect_b32 s101, s53, s101
	s_bitcmp1_b32 s28, 12
	s_cselect_b32 s100, s100, s14
	s_cselect_b32 s101, s101, s15
	v_lshl_add_u64 v[242:243], s[100:101], 0, v[250:251]
	s_mov_b32 m0, 0x21800
	s_mov_b64 exec, 0xff
	s_nop 0
	global_load_lds_dword v[242:243], off
	s_mov_b64 exec, -1
	s_waitcnt vmcnt(9)
	s_waitcnt lgkmcnt(0)
	s_barrier
	v_mfma_f32_16x16x32_bf16 v[62:65], v[152:155], v[194:197], v[62:65]
	v_mfma_f32_16x16x32_bf16 v[62:65], v[162:165], v[198:201], v[62:65]
	v_mfma_f32_16x16x32_bf16 v[58:61], v[166:169], v[194:197], v[58:61]
	v_mfma_f32_16x16x32_bf16 v[58:61], v[170:173], v[198:201], v[58:61]
	v_mfma_f32_16x16x32_bf16 v[46:49], v[152:155], v[202:205], v[46:49]
	v_mfma_f32_16x16x32_bf16 v[46:49], v[162:165], v[206:209], v[46:49]
	v_mfma_f32_16x16x32_bf16 v[42:45], v[166:169], v[202:205], v[42:45]
	v_mfma_f32_16x16x32_bf16 v[42:45], v[170:173], v[206:209], v[42:45]
	v_mfma_f32_16x16x32_bf16 v[30:33], v[152:155], v[210:213], v[30:33]
	v_mfma_f32_16x16x32_bf16 v[30:33], v[162:165], v[214:217], v[30:33]
	v_mfma_f32_16x16x32_bf16 v[26:29], v[166:169], v[210:213], v[26:29]
	v_mfma_f32_16x16x32_bf16 v[26:29], v[170:173], v[214:217], v[26:29]
	v_mfma_f32_16x16x32_bf16 v[14:17], v[152:155], v[218:221], v[14:17]
	v_mfma_f32_16x16x32_bf16 v[14:17], v[162:165], v[222:225], v[14:17]
	v_mfma_f32_16x16x32_bf16 v[10:13], v[166:169], v[218:221], v[10:13]
	v_mfma_f32_16x16x32_bf16 v[10:13], v[170:173], v[222:225], v[10:13]
	v_mfma_f32_16x16x32_bf16 v[54:57], v[174:177], v[194:197], v[54:57]
	v_mfma_f32_16x16x32_bf16 v[54:57], v[182:185], v[198:201], v[54:57]
	v_mfma_f32_16x16x32_bf16 v[50:53], v[186:189], v[194:197], v[50:53]
	v_mfma_f32_16x16x32_bf16 v[50:53], v[190:193], v[198:201], v[50:53]
	v_mfma_f32_16x16x32_bf16 v[38:41], v[174:177], v[202:205], v[38:41]
	v_mfma_f32_16x16x32_bf16 v[38:41], v[182:185], v[206:209], v[38:41]
	v_mfma_f32_16x16x32_bf16 v[34:37], v[186:189], v[202:205], v[34:37]
	v_mfma_f32_16x16x32_bf16 v[34:37], v[190:193], v[206:209], v[34:37]
	v_mfma_f32_16x16x32_bf16 v[22:25], v[174:177], v[210:213], v[22:25]
	v_mfma_f32_16x16x32_bf16 v[22:25], v[182:185], v[214:217], v[22:25]
	v_mfma_f32_16x16x32_bf16 v[18:21], v[186:189], v[210:213], v[18:21]
	v_mfma_f32_16x16x32_bf16 v[18:21], v[190:193], v[214:217], v[18:21]
	v_mfma_f32_16x16x32_bf16 v[6:9], v[174:177], v[218:221], v[6:9]
	v_mfma_f32_16x16x32_bf16 v[6:9], v[182:185], v[222:225], v[6:9]
	v_mfma_f32_16x16x32_bf16 v[2:5], v[186:189], v[218:221], v[2:5]
	v_mfma_f32_16x16x32_bf16 v[2:5], v[190:193], v[222:225], v[2:5]
	s_barrier
	s_add_u32 s100, s16, 0x100000
	s_addc_u32 s101, s17, 0
	s_mov_b32 m0, s29
	ds_read_b128 v[152:155], v252 offset:32768
	ds_read_b128 v[162:165], v252 offset:33792
	global_load_lds_dwordx4 v146, s[100:101]
	s_mov_b32 m0, s36
	ds_read_b128 v[166:169], v252 offset:34816
	ds_read_b128 v[170:173], v252 offset:35840
	global_load_lds_dwordx4 v142, s[100:101]
	ds_read_b128 v[174:177], v252 offset:49152
	ds_read_b128 v[182:185], v252 offset:50176
	ds_read_b128 v[186:189], v252 offset:51200
	ds_read_b128 v[190:193], v252 offset:52224
	ds_read_b128 v[194:197], v161 offset:32768
	ds_read_b128 v[198:201], v161 offset:33792
	ds_read_b128 v[202:205], v161 offset:34816
	ds_read_b128 v[206:209], v161 offset:35840
	ds_read_b128 v[210:213], v161 offset:36864
	ds_read_b128 v[214:217], v161 offset:37888
	ds_read_b128 v[218:221], v161 offset:38912
	ds_read_b128 v[222:225], v161 offset:39936
	s_waitcnt vmcnt(9)
	s_waitcnt lgkmcnt(0)
	s_barrier
	v_mfma_f32_16x16x32_bf16 v[126:129], v[152:155], v[194:197], v[126:129]
	v_mfma_f32_16x16x32_bf16 v[126:129], v[162:165], v[198:201], v[126:129]
	v_mfma_f32_16x16x32_bf16 v[122:125], v[166:169], v[194:197], v[122:125]
	v_mfma_f32_16x16x32_bf16 v[122:125], v[170:173], v[198:201], v[122:125]
	v_mfma_f32_16x16x32_bf16 v[110:113], v[152:155], v[202:205], v[110:113]
	v_mfma_f32_16x16x32_bf16 v[110:113], v[162:165], v[206:209], v[110:113]
	v_mfma_f32_16x16x32_bf16 v[106:109], v[166:169], v[202:205], v[106:109]
	v_mfma_f32_16x16x32_bf16 v[106:109], v[170:173], v[206:209], v[106:109]
	v_mfma_f32_16x16x32_bf16 v[94:97], v[152:155], v[210:213], v[94:97]
	v_mfma_f32_16x16x32_bf16 v[94:97], v[162:165], v[214:217], v[94:97]
	v_mfma_f32_16x16x32_bf16 v[90:93], v[166:169], v[210:213], v[90:93]
	v_mfma_f32_16x16x32_bf16 v[90:93], v[170:173], v[214:217], v[90:93]
	v_mfma_f32_16x16x32_bf16 v[78:81], v[152:155], v[218:221], v[78:81]
	v_mfma_f32_16x16x32_bf16 v[78:81], v[162:165], v[222:225], v[78:81]
	v_mfma_f32_16x16x32_bf16 v[74:77], v[166:169], v[218:221], v[74:77]
	v_mfma_f32_16x16x32_bf16 v[74:77], v[170:173], v[222:225], v[74:77]
	v_mfma_f32_16x16x32_bf16 v[118:121], v[174:177], v[194:197], v[118:121]
	v_mfma_f32_16x16x32_bf16 v[118:121], v[182:185], v[198:201], v[118:121]
	v_mfma_f32_16x16x32_bf16 v[114:117], v[186:189], v[194:197], v[114:117]
	v_mfma_f32_16x16x32_bf16 v[114:117], v[190:193], v[198:201], v[114:117]
	v_mfma_f32_16x16x32_bf16 v[102:105], v[174:177], v[202:205], v[102:105]
	v_mfma_f32_16x16x32_bf16 v[102:105], v[182:185], v[206:209], v[102:105]
	v_mfma_f32_16x16x32_bf16 v[98:101], v[186:189], v[202:205], v[98:101]
	v_mfma_f32_16x16x32_bf16 v[98:101], v[190:193], v[206:209], v[98:101]
	v_mfma_f32_16x16x32_bf16 v[86:89], v[174:177], v[210:213], v[86:89]
	v_mfma_f32_16x16x32_bf16 v[86:89], v[182:185], v[214:217], v[86:89]
	v_mfma_f32_16x16x32_bf16 v[82:85], v[186:189], v[210:213], v[82:85]
	v_mfma_f32_16x16x32_bf16 v[82:85], v[190:193], v[214:217], v[82:85]
	v_mfma_f32_16x16x32_bf16 v[70:73], v[174:177], v[218:221], v[70:73]
	v_mfma_f32_16x16x32_bf16 v[70:73], v[182:185], v[222:225], v[70:73]
	v_mfma_f32_16x16x32_bf16 v[66:69], v[186:189], v[218:221], v[66:69]
	v_mfma_f32_16x16x32_bf16 v[66:69], v[190:193], v[222:225], v[66:69]
	s_barrier
	s_add_u32 s14, s14, 0x80
	s_addc_u32 s15, s15, 0
	s_add_i32 m0, s28, 0x18000
	ds_read_b128 v[194:197], v161 offset:49152
	ds_read_b128 v[198:201], v161 offset:50176
	global_load_lds_dwordx4 v144, s[14:15]
	s_add_i32 m0, s28, 0x1a000
	s_add_u32 s98, s98, 0x80
	s_addc_u32 s99, s99, 0
	ds_read_b128 v[202:205], v161 offset:51200
	global_load_lds_dwordx4 v140, s[14:15]
	s_add_i32 m0, s28, 0x1c000
	ds_read_b128 v[206:209], v161 offset:52224
	ds_read_b128 v[210:213], v161 offset:53248
	global_load_lds_dwordx4 v144, s[98:99]
	s_add_i32 m0, s28, 0x1e000
	s_add_u32 s16, s16, 0x80
	s_addc_u32 s17, s17, 0
	ds_read_b128 v[214:217], v161 offset:54272
	ds_read_b128 v[218:221], v161 offset:55296
	global_load_lds_dwordx4 v140, s[98:99]
	s_mov_b32 m0, s45
	ds_read_b128 v[222:225], v161 offset:56320
	global_load_lds_dwordx4 v146, s[16:17]
	s_mov_b32 m0, s46
	s_nop 0
	global_load_lds_dwordx4 v142, s[16:17]
	s_waitcnt vmcnt(9)
	s_waitcnt lgkmcnt(0)
	s_barrier
	v_mfma_f32_16x16x32_bf16 v[62:65], v[152:155], v[194:197], v[62:65]
	v_mfma_f32_16x16x32_bf16 v[62:65], v[162:165], v[198:201], v[62:65]
	v_mfma_f32_16x16x32_bf16 v[58:61], v[166:169], v[194:197], v[58:61]
	v_mfma_f32_16x16x32_bf16 v[58:61], v[170:173], v[198:201], v[58:61]
	v_mfma_f32_16x16x32_bf16 v[46:49], v[152:155], v[202:205], v[46:49]
	v_mfma_f32_16x16x32_bf16 v[46:49], v[162:165], v[206:209], v[46:49]
	v_mfma_f32_16x16x32_bf16 v[42:45], v[166:169], v[202:205], v[42:45]
	v_mfma_f32_16x16x32_bf16 v[42:45], v[170:173], v[206:209], v[42:45]
	v_mfma_f32_16x16x32_bf16 v[30:33], v[152:155], v[210:213], v[30:33]
	v_mfma_f32_16x16x32_bf16 v[30:33], v[162:165], v[214:217], v[30:33]
	v_mfma_f32_16x16x32_bf16 v[26:29], v[166:169], v[210:213], v[26:29]
	v_mfma_f32_16x16x32_bf16 v[26:29], v[170:173], v[214:217], v[26:29]
	v_mfma_f32_16x16x32_bf16 v[14:17], v[152:155], v[218:221], v[14:17]
	v_mfma_f32_16x16x32_bf16 v[14:17], v[162:165], v[222:225], v[14:17]
	v_mfma_f32_16x16x32_bf16 v[10:13], v[166:169], v[218:221], v[10:13]
	v_mfma_f32_16x16x32_bf16 v[10:13], v[170:173], v[222:225], v[10:13]
	v_mfma_f32_16x16x32_bf16 v[54:57], v[174:177], v[194:197], v[54:57]
	v_mfma_f32_16x16x32_bf16 v[54:57], v[182:185], v[198:201], v[54:57]
	v_mfma_f32_16x16x32_bf16 v[50:53], v[186:189], v[194:197], v[50:53]
	v_mfma_f32_16x16x32_bf16 v[50:53], v[190:193], v[198:201], v[50:53]
	v_mfma_f32_16x16x32_bf16 v[38:41], v[174:177], v[202:205], v[38:41]
	v_mfma_f32_16x16x32_bf16 v[38:41], v[182:185], v[206:209], v[38:41]
	v_mfma_f32_16x16x32_bf16 v[34:37], v[186:189], v[202:205], v[34:37]
	v_mfma_f32_16x16x32_bf16 v[34:37], v[190:193], v[206:209], v[34:37]
	v_mfma_f32_16x16x32_bf16 v[22:25], v[174:177], v[210:213], v[22:25]
	v_mfma_f32_16x16x32_bf16 v[22:25], v[182:185], v[214:217], v[22:25]
	v_mfma_f32_16x16x32_bf16 v[18:21], v[186:189], v[210:213], v[18:21]
	v_mfma_f32_16x16x32_bf16 v[18:21], v[190:193], v[214:217], v[18:21]
	v_mfma_f32_16x16x32_bf16 v[6:9], v[174:177], v[218:221], v[6:9]
	v_mfma_f32_16x16x32_bf16 v[6:9], v[182:185], v[222:225], v[6:9]
	v_mfma_f32_16x16x32_bf16 v[2:5], v[186:189], v[218:221], v[2:5]
	v_mfma_f32_16x16x32_bf16 v[2:5], v[190:193], v[222:225], v[2:5]
	s_barrier
	s_add_i32 s39, s39, 2
	s_add_u32 s12, s12, 0x100
	s_addc_u32 s13, s13, 0
	s_add_u32 s0, s0, 0x100
	s_addc_u32 s1, s1, 0
	s_cmp_gt_u32 s39, 61
	s_cbranch_scc0 .LBB0_341
	s_and_b64 vcc, exec, s[34:35]
	s_cbranch_vccz .LBB0_344
	s_barrier

.LBB0_572:
	s_add_u32 s14, s12, 0xfff00080
	s_addc_u32 s15, s13, -1
	s_cmp_eq_u32 s35, 60
	s_cselect_b32 s17, s51, s15
	s_cselect_b32 s16, s50, s14
	s_cselect_b32 s15, s53, s1
	s_cselect_b32 s14, s52, s0
	s_add_i32 m0, s8, 0xc000
	ds_read_b128 v[152:155], v252
	ds_read_b128 v[162:165], v252 offset:1024
	global_load_lds_dwordx4 v148, s[12:13]
	s_add_i32 m0, s8, 0xe000
	ds_read_b128 v[166:169], v252 offset:2048
	ds_read_b128 v[170:173], v252 offset:3072
	global_load_lds_dwordx4 v150, s[12:13]
	ds_read_b128 v[174:177], v252 offset:16384
	ds_read_b128 v[182:185], v252 offset:17408
	ds_read_b128 v[186:189], v252 offset:18432
	ds_read_b128 v[190:193], v252 offset:19456
	ds_read_b128 v[194:197], v161
	ds_read_b128 v[198:201], v161 offset:1024
	ds_read_b128 v[202:205], v161 offset:2048
	ds_read_b128 v[206:209], v161 offset:3072
	ds_read_b128 v[210:213], v161 offset:4096
	ds_read_b128 v[214:217], v161 offset:5120
	ds_read_b128 v[218:221], v161 offset:6144
	ds_read_b128 v[222:225], v161 offset:7168
	s_waitcnt vmcnt(8)
	s_waitcnt lgkmcnt(0)
	s_barrier
	v_mfma_f32_16x16x32_bf16 v[126:129], v[152:155], v[194:197], v[126:129]
	v_mfma_f32_16x16x32_bf16 v[126:129], v[162:165], v[198:201], v[126:129]
	v_mfma_f32_16x16x32_bf16 v[122:125], v[166:169], v[194:197], v[122:125]
	v_mfma_f32_16x16x32_bf16 v[122:125], v[170:173], v[198:201], v[122:125]
	v_mfma_f32_16x16x32_bf16 v[110:113], v[152:155], v[202:205], v[110:113]
	v_mfma_f32_16x16x32_bf16 v[110:113], v[162:165], v[206:209], v[110:113]
	v_mfma_f32_16x16x32_bf16 v[106:109], v[166:169], v[202:205], v[106:109]
	v_mfma_f32_16x16x32_bf16 v[106:109], v[170:173], v[206:209], v[106:109]
	v_mfma_f32_16x16x32_bf16 v[94:97], v[152:155], v[210:213], v[94:97]
	v_mfma_f32_16x16x32_bf16 v[94:97], v[162:165], v[214:217], v[94:97]
	v_mfma_f32_16x16x32_bf16 v[90:93], v[166:169], v[210:213], v[90:93]
	v_mfma_f32_16x16x32_bf16 v[90:93], v[170:173], v[214:217], v[90:93]
	v_mfma_f32_16x16x32_bf16 v[78:81], v[152:155], v[218:221], v[78:81]
	v_mfma_f32_16x16x32_bf16 v[78:81], v[162:165], v[222:225], v[78:81]
	v_mfma_f32_16x16x32_bf16 v[74:77], v[166:169], v[218:221], v[74:77]
	v_mfma_f32_16x16x32_bf16 v[74:77], v[170:173], v[222:225], v[74:77]
	v_mfma_f32_16x16x32_bf16 v[118:121], v[174:177], v[194:197], v[118:121]
	v_mfma_f32_16x16x32_bf16 v[118:121], v[182:185], v[198:201], v[118:121]
	v_mfma_f32_16x16x32_bf16 v[114:117], v[186:189], v[194:197], v[114:117]
	v_mfma_f32_16x16x32_bf16 v[114:117], v[190:193], v[198:201], v[114:117]
	v_mfma_f32_16x16x32_bf16 v[102:105], v[174:177], v[202:205], v[102:105]
	v_mfma_f32_16x16x32_bf16 v[102:105], v[182:185], v[206:209], v[102:105]
	v_mfma_f32_16x16x32_bf16 v[98:101], v[186:189], v[202:205], v[98:101]
	v_mfma_f32_16x16x32_bf16 v[98:101], v[190:193], v[206:209], v[98:101]
	v_mfma_f32_16x16x32_bf16 v[86:89], v[174:177], v[210:213], v[86:89]
	v_mfma_f32_16x16x32_bf16 v[86:89], v[182:185], v[214:217], v[86:89]
	v_mfma_f32_16x16x32_bf16 v[82:85], v[186:189], v[210:213], v[82:85]
	v_mfma_f32_16x16x32_bf16 v[82:85], v[190:193], v[214:217], v[82:85]
	v_mfma_f32_16x16x32_bf16 v[70:73], v[174:177], v[218:221], v[70:73]
	v_mfma_f32_16x16x32_bf16 v[70:73], v[182:185], v[222:225], v[70:73]
	v_mfma_f32_16x16x32_bf16 v[66:69], v[186:189], v[218:221], v[66:69]
	v_mfma_f32_16x16x32_bf16 v[66:69], v[190:193], v[222:225], v[66:69]
	s_barrier
	s_add_i32 m0, s28, 0x10000
	ds_read_b128 v[194:197], v161 offset:16384
	ds_read_b128 v[198:201], v161 offset:17408
	global_load_lds_dwordx4 v144, s[14:15]
	s_add_i32 m0, s28, 0x12000
	s_add_u32 s98, s14, 0x100000
	s_addc_u32 s99, s15, 0
	ds_read_b128 v[202:205], v161 offset:18432
	global_load_lds_dwordx4 v140, s[14:15]
	s_add_i32 m0, s28, 0x14000
	ds_read_b128 v[206:209], v161 offset:19456
	ds_read_b128 v[210:213], v161 offset:20480
	global_load_lds_dwordx4 v144, s[98:99]
	s_add_i32 m0, s28, 0x16000
	ds_read_b128 v[214:217], v161 offset:21504
	ds_read_b128 v[218:221], v161 offset:22528
	global_load_lds_dwordx4 v140, s[98:99]
	s_mov_b32 m0, s8
	ds_read_b128 v[222:225], v161 offset:23552
	global_load_lds_dwordx4 v146, s[16:17]
	s_mov_b32 m0, s9
	s_nop 0
	global_load_lds_dwordx4 v142, s[16:17]
	s_add_u32 s100, s14, 0x100
	s_addc_u32 s101, s15, 0
	s_cmp_eq_u32 s35, 58
	s_cselect_b32 s100, s52, s100
	s_cselect_b32 s101, s53, s101
	s_bitcmp1_b32 s28, 12
	s_cselect_b32 s100, s100, s14
	s_cselect_b32 s101, s101, s15
	v_lshl_add_u64 v[242:243], s[100:101], 0, v[250:251]
	s_mov_b32 m0, 0x21800
	s_mov_b64 exec, 0xff
	s_nop 0
	global_load_lds_dword v[242:243], off
	s_mov_b64 exec, -1
	s_waitcnt vmcnt(9)
	s_waitcnt lgkmcnt(0)
	s_barrier
	v_mfma_f32_16x16x32_bf16 v[62:65], v[152:155], v[194:197], v[62:65]
	v_mfma_f32_16x16x32_bf16 v[62:65], v[162:165], v[198:201], v[62:65]
	v_mfma_f32_16x16x32_bf16 v[58:61], v[166:169], v[194:197], v[58:61]
	v_mfma_f32_16x16x32_bf16 v[58:61], v[170:173], v[198:201], v[58:61]
	v_mfma_f32_16x16x32_bf16 v[46:49], v[152:155], v[202:205], v[46:49]
	v_mfma_f32_16x16x32_bf16 v[46:49], v[162:165], v[206:209], v[46:49]
	v_mfma_f32_16x16x32_bf16 v[42:45], v[166:169], v[202:205], v[42:45]
	v_mfma_f32_16x16x32_bf16 v[42:45], v[170:173], v[206:209], v[42:45]
	v_mfma_f32_16x16x32_bf16 v[30:33], v[152:155], v[210:213], v[30:33]
	v_mfma_f32_16x16x32_bf16 v[30:33], v[162:165], v[214:217], v[30:33]
	v_mfma_f32_16x16x32_bf16 v[26:29], v[166:169], v[210:213], v[26:29]
	v_mfma_f32_16x16x32_bf16 v[26:29], v[170:173], v[214:217], v[26:29]
	v_mfma_f32_16x16x32_bf16 v[14:17], v[152:155], v[218:221], v[14:17]
	v_mfma_f32_16x16x32_bf16 v[14:17], v[162:165], v[222:225], v[14:17]
	v_mfma_f32_16x16x32_bf16 v[10:13], v[166:169], v[218:221], v[10:13]
	v_mfma_f32_16x16x32_bf16 v[10:13], v[170:173], v[222:225], v[10:13]
	v_mfma_f32_16x16x32_bf16 v[54:57], v[174:177], v[194:197], v[54:57]
	v_mfma_f32_16x16x32_bf16 v[54:57], v[182:185], v[198:201], v[54:57]
	v_mfma_f32_16x16x32_bf16 v[50:53], v[186:189], v[194:197], v[50:53]
	v_mfma_f32_16x16x32_bf16 v[50:53], v[190:193], v[198:201], v[50:53]
	v_mfma_f32_16x16x32_bf16 v[38:41], v[174:177], v[202:205], v[38:41]
	v_mfma_f32_16x16x32_bf16 v[38:41], v[182:185], v[206:209], v[38:41]
	v_mfma_f32_16x16x32_bf16 v[34:37], v[186:189], v[202:205], v[34:37]
	v_mfma_f32_16x16x32_bf16 v[34:37], v[190:193], v[206:209], v[34:37]
	v_mfma_f32_16x16x32_bf16 v[22:25], v[174:177], v[210:213], v[22:25]
	v_mfma_f32_16x16x32_bf16 v[22:25], v[182:185], v[214:217], v[22:25]
	v_mfma_f32_16x16x32_bf16 v[18:21], v[186:189], v[210:213], v[18:21]
	v_mfma_f32_16x16x32_bf16 v[18:21], v[190:193], v[214:217], v[18:21]
	v_mfma_f32_16x16x32_bf16 v[6:9], v[174:177], v[218:221], v[6:9]
	v_mfma_f32_16x16x32_bf16 v[6:9], v[182:185], v[222:225], v[6:9]
	v_mfma_f32_16x16x32_bf16 v[2:5], v[186:189], v[218:221], v[2:5]
	v_mfma_f32_16x16x32_bf16 v[2:5], v[190:193], v[222:225], v[2:5]
	s_barrier
	s_add_u32 s100, s16, 0x100000
	s_addc_u32 s101, s17, 0
	s_mov_b32 m0, s29
	ds_read_b128 v[152:155], v252 offset:32768
	ds_read_b128 v[162:165], v252 offset:33792
	global_load_lds_dwordx4 v146, s[100:101]
	s_mov_b32 m0, s36
	ds_read_b128 v[166:169], v252 offset:34816
	ds_read_b128 v[170:173], v252 offset:35840
	global_load_lds_dwordx4 v142, s[100:101]
	ds_read_b128 v[174:177], v252 offset:49152
	ds_read_b128 v[182:185], v252 offset:50176
	ds_read_b128 v[186:189], v252 offset:51200
	ds_read_b128 v[190:193], v252 offset:52224
	ds_read_b128 v[194:197], v161 offset:32768
	ds_read_b128 v[198:201], v161 offset:33792
	ds_read_b128 v[202:205], v161 offset:34816
	ds_read_b128 v[206:209], v161 offset:35840
	ds_read_b128 v[210:213], v161 offset:36864
	ds_read_b128 v[214:217], v161 offset:37888
	ds_read_b128 v[218:221], v161 offset:38912
	ds_read_b128 v[222:225], v161 offset:39936
	s_waitcnt vmcnt(9)
	s_waitcnt lgkmcnt(0)
	s_barrier
	v_mfma_f32_16x16x32_bf16 v[126:129], v[152:155], v[194:197], v[126:129]
	v_mfma_f32_16x16x32_bf16 v[126:129], v[162:165], v[198:201], v[126:129]
	v_mfma_f32_16x16x32_bf16 v[122:125], v[166:169], v[194:197], v[122:125]
	v_mfma_f32_16x16x32_bf16 v[122:125], v[170:173], v[198:201], v[122:125]
	v_mfma_f32_16x16x32_bf16 v[110:113], v[152:155], v[202:205], v[110:113]
	v_mfma_f32_16x16x32_bf16 v[110:113], v[162:165], v[206:209], v[110:113]
	v_mfma_f32_16x16x32_bf16 v[106:109], v[166:169], v[202:205], v[106:109]
	v_mfma_f32_16x16x32_bf16 v[106:109], v[170:173], v[206:209], v[106:109]
	v_mfma_f32_16x16x32_bf16 v[94:97], v[152:155], v[210:213], v[94:97]
	v_mfma_f32_16x16x32_bf16 v[94:97], v[162:165], v[214:217], v[94:97]
	v_mfma_f32_16x16x32_bf16 v[90:93], v[166:169], v[210:213], v[90:93]
	v_mfma_f32_16x16x32_bf16 v[90:93], v[170:173], v[214:217], v[90:93]
	v_mfma_f32_16x16x32_bf16 v[78:81], v[152:155], v[218:221], v[78:81]
	v_mfma_f32_16x16x32_bf16 v[78:81], v[162:165], v[222:225], v[78:81]
	v_mfma_f32_16x16x32_bf16 v[74:77], v[166:169], v[218:221], v[74:77]
	v_mfma_f32_16x16x32_bf16 v[74:77], v[170:173], v[222:225], v[74:77]
	v_mfma_f32_16x16x32_bf16 v[118:121], v[174:177], v[194:197], v[118:121]
	v_mfma_f32_16x16x32_bf16 v[118:121], v[182:185], v[198:201], v[118:121]
	v_mfma_f32_16x16x32_bf16 v[114:117], v[186:189], v[194:197], v[114:117]
	v_mfma_f32_16x16x32_bf16 v[114:117], v[190:193], v[198:201], v[114:117]
	v_mfma_f32_16x16x32_bf16 v[102:105], v[174:177], v[202:205], v[102:105]
	v_mfma_f32_16x16x32_bf16 v[102:105], v[182:185], v[206:209], v[102:105]
	v_mfma_f32_16x16x32_bf16 v[98:101], v[186:189], v[202:205], v[98:101]
	v_mfma_f32_16x16x32_bf16 v[98:101], v[190:193], v[206:209], v[98:101]
	v_mfma_f32_16x16x32_bf16 v[86:89], v[174:177], v[210:213], v[86:89]
	v_mfma_f32_16x16x32_bf16 v[86:89], v[182:185], v[214:217], v[86:89]
	v_mfma_f32_16x16x32_bf16 v[82:85], v[186:189], v[210:213], v[82:85]
	v_mfma_f32_16x16x32_bf16 v[82:85], v[190:193], v[214:217], v[82:85]
	v_mfma_f32_16x16x32_bf16 v[70:73], v[174:177], v[218:221], v[70:73]
	v_mfma_f32_16x16x32_bf16 v[70:73], v[182:185], v[222:225], v[70:73]
	v_mfma_f32_16x16x32_bf16 v[66:69], v[186:189], v[218:221], v[66:69]
	v_mfma_f32_16x16x32_bf16 v[66:69], v[190:193], v[222:225], v[66:69]
	s_barrier
	s_add_u32 s14, s14, 0x80
	s_addc_u32 s15, s15, 0
	s_add_i32 m0, s28, 0x18000
	ds_read_b128 v[194:197], v161 offset:49152
	ds_read_b128 v[198:201], v161 offset:50176
	global_load_lds_dwordx4 v144, s[14:15]
	s_add_i32 m0, s28, 0x1a000
	s_add_u32 s98, s98, 0x80
	s_addc_u32 s99, s99, 0
	ds_read_b128 v[202:205], v161 offset:51200
	global_load_lds_dwordx4 v140, s[14:15]
	s_add_i32 m0, s28, 0x1c000
	ds_read_b128 v[206:209], v161 offset:52224
	ds_read_b128 v[210:213], v161 offset:53248
	global_load_lds_dwordx4 v144, s[98:99]
	s_add_i32 m0, s28, 0x1e000
	s_add_u32 s16, s16, 0x80
	s_addc_u32 s17, s17, 0
	ds_read_b128 v[214:217], v161 offset:54272
	ds_read_b128 v[218:221], v161 offset:55296
	global_load_lds_dwordx4 v140, s[98:99]
	s_mov_b32 m0, s39
	ds_read_b128 v[222:225], v161 offset:56320
	global_load_lds_dwordx4 v146, s[16:17]
	s_mov_b32 m0, s44
	s_nop 0
	global_load_lds_dwordx4 v142, s[16:17]
	s_waitcnt vmcnt(9)
	s_waitcnt lgkmcnt(0)
	s_barrier
	v_mfma_f32_16x16x32_bf16 v[62:65], v[152:155], v[194:197], v[62:65]
	v_mfma_f32_16x16x32_bf16 v[62:65], v[162:165], v[198:201], v[62:65]
	v_mfma_f32_16x16x32_bf16 v[58:61], v[166:169], v[194:197], v[58:61]
	v_mfma_f32_16x16x32_bf16 v[58:61], v[170:173], v[198:201], v[58:61]
	v_mfma_f32_16x16x32_bf16 v[46:49], v[152:155], v[202:205], v[46:49]
	v_mfma_f32_16x16x32_bf16 v[46:49], v[162:165], v[206:209], v[46:49]
	v_mfma_f32_16x16x32_bf16 v[42:45], v[166:169], v[202:205], v[42:45]
	v_mfma_f32_16x16x32_bf16 v[42:45], v[170:173], v[206:209], v[42:45]
	v_mfma_f32_16x16x32_bf16 v[30:33], v[152:155], v[210:213], v[30:33]
	v_mfma_f32_16x16x32_bf16 v[30:33], v[162:165], v[214:217], v[30:33]
	v_mfma_f32_16x16x32_bf16 v[26:29], v[166:169], v[210:213], v[26:29]
	v_mfma_f32_16x16x32_bf16 v[26:29], v[170:173], v[214:217], v[26:29]
	v_mfma_f32_16x16x32_bf16 v[14:17], v[152:155], v[218:221], v[14:17]
	v_mfma_f32_16x16x32_bf16 v[14:17], v[162:165], v[222:225], v[14:17]
	v_mfma_f32_16x16x32_bf16 v[10:13], v[166:169], v[218:221], v[10:13]
	v_mfma_f32_16x16x32_bf16 v[10:13], v[170:173], v[222:225], v[10:13]
	v_mfma_f32_16x16x32_bf16 v[54:57], v[174:177], v[194:197], v[54:57]
	v_mfma_f32_16x16x32_bf16 v[54:57], v[182:185], v[198:201], v[54:57]
	v_mfma_f32_16x16x32_bf16 v[50:53], v[186:189], v[194:197], v[50:53]
	v_mfma_f32_16x16x32_bf16 v[50:53], v[190:193], v[198:201], v[50:53]
	v_mfma_f32_16x16x32_bf16 v[38:41], v[174:177], v[202:205], v[38:41]
	v_mfma_f32_16x16x32_bf16 v[38:41], v[182:185], v[206:209], v[38:41]
	v_mfma_f32_16x16x32_bf16 v[34:37], v[186:189], v[202:205], v[34:37]
	v_mfma_f32_16x16x32_bf16 v[34:37], v[190:193], v[206:209], v[34:37]
	v_mfma_f32_16x16x32_bf16 v[22:25], v[174:177], v[210:213], v[22:25]
	v_mfma_f32_16x16x32_bf16 v[22:25], v[182:185], v[214:217], v[22:25]
	v_mfma_f32_16x16x32_bf16 v[18:21], v[186:189], v[210:213], v[18:21]
	v_mfma_f32_16x16x32_bf16 v[18:21], v[190:193], v[214:217], v[18:21]
	v_mfma_f32_16x16x32_bf16 v[6:9], v[174:177], v[218:221], v[6:9]
	v_mfma_f32_16x16x32_bf16 v[6:9], v[182:185], v[222:225], v[6:9]
	v_mfma_f32_16x16x32_bf16 v[2:5], v[186:189], v[218:221], v[2:5]
	v_mfma_f32_16x16x32_bf16 v[2:5], v[190:193], v[222:225], v[2:5]
	s_barrier
	s_add_i32 s35, s35, 2
	s_add_u32 s12, s12, 0x100
	s_addc_u32 s13, s13, 0
	s_add_u32 s0, s0, 0x100
	s_addc_u32 s1, s1, 0
	s_cmp_gt_u32 s35, 61
	s_cbranch_scc0 .LBB0_572
	s_and_b64 vcc, exec, s[10:11]
	s_cbranch_vccz .LBB0_575
	s_barrier

.LBB0_882:
	s_add_u32 s20, s10, 0xfff00080
	s_addc_u32 s21, s11, -1
	s_cmp_eq_u32 s12, 60
	s_cselect_b32 s43, s55, s21
	s_cselect_b32 s42, s54, s20
	s_cselect_b32 s39, s37, s1
	s_cselect_b32 s38, s36, s0
	s_add_i32 m0, s29, 0xc000
	ds_read_b128 v[146:149], v252
	ds_read_b128 v[150:153], v252 offset:1024
	global_load_lds_dwordx4 v140, s[10:11]
	s_add_i32 m0, s29, 0xe000
	ds_read_b128 v[158:161], v252 offset:2048
	ds_read_b128 v[162:165], v252 offset:3072
	global_load_lds_dwordx4 v142, s[10:11]
	ds_read_b128 v[166:169], v252 offset:16384
	ds_read_b128 v[170:173], v252 offset:17408
	ds_read_b128 v[174:177], v252 offset:18432
	ds_read_b128 v[186:189], v252 offset:19456
	ds_read_b128 v[190:193], v157
	ds_read_b128 v[194:197], v157 offset:1024
	ds_read_b128 v[198:201], v157 offset:2048
	ds_read_b128 v[202:205], v157 offset:3072
	ds_read_b128 v[206:209], v157 offset:4096
	ds_read_b128 v[210:213], v157 offset:5120
	ds_read_b128 v[214:217], v157 offset:6144
	ds_read_b128 v[218:221], v157 offset:7168
	s_waitcnt vmcnt(8)
	s_waitcnt lgkmcnt(0)
	s_barrier
	v_mfma_f32_16x16x32_bf16 v[128:131], v[146:149], v[190:193], v[128:131]
	v_mfma_f32_16x16x32_bf16 v[128:131], v[150:153], v[194:197], v[128:131]
	v_mfma_f32_16x16x32_bf16 v[124:127], v[158:161], v[190:193], v[124:127]
	v_mfma_f32_16x16x32_bf16 v[124:127], v[162:165], v[194:197], v[124:127]
	v_mfma_f32_16x16x32_bf16 v[112:115], v[146:149], v[198:201], v[112:115]
	v_mfma_f32_16x16x32_bf16 v[112:115], v[150:153], v[202:205], v[112:115]
	v_mfma_f32_16x16x32_bf16 v[108:111], v[158:161], v[198:201], v[108:111]
	v_mfma_f32_16x16x32_bf16 v[108:111], v[162:165], v[202:205], v[108:111]
	v_mfma_f32_16x16x32_bf16 v[96:99], v[146:149], v[206:209], v[96:99]
	v_mfma_f32_16x16x32_bf16 v[96:99], v[150:153], v[210:213], v[96:99]
	v_mfma_f32_16x16x32_bf16 v[92:95], v[158:161], v[206:209], v[92:95]
	v_mfma_f32_16x16x32_bf16 v[92:95], v[162:165], v[210:213], v[92:95]
	v_mfma_f32_16x16x32_bf16 v[80:83], v[146:149], v[214:217], v[80:83]
	v_mfma_f32_16x16x32_bf16 v[80:83], v[150:153], v[218:221], v[80:83]
	v_mfma_f32_16x16x32_bf16 v[76:79], v[158:161], v[214:217], v[76:79]
	v_mfma_f32_16x16x32_bf16 v[76:79], v[162:165], v[218:221], v[76:79]
	v_mfma_f32_16x16x32_bf16 v[120:123], v[166:169], v[190:193], v[120:123]
	v_mfma_f32_16x16x32_bf16 v[120:123], v[170:173], v[194:197], v[120:123]
	v_mfma_f32_16x16x32_bf16 v[116:119], v[174:177], v[190:193], v[116:119]
	v_mfma_f32_16x16x32_bf16 v[116:119], v[186:189], v[194:197], v[116:119]
	v_mfma_f32_16x16x32_bf16 v[104:107], v[166:169], v[198:201], v[104:107]
	v_mfma_f32_16x16x32_bf16 v[104:107], v[170:173], v[202:205], v[104:107]
	v_mfma_f32_16x16x32_bf16 v[100:103], v[174:177], v[198:201], v[100:103]
	v_mfma_f32_16x16x32_bf16 v[100:103], v[186:189], v[202:205], v[100:103]
	v_mfma_f32_16x16x32_bf16 v[88:91], v[166:169], v[206:209], v[88:91]
	v_mfma_f32_16x16x32_bf16 v[88:91], v[170:173], v[210:213], v[88:91]
	v_mfma_f32_16x16x32_bf16 v[84:87], v[174:177], v[206:209], v[84:87]
	v_mfma_f32_16x16x32_bf16 v[84:87], v[186:189], v[210:213], v[84:87]
	v_mfma_f32_16x16x32_bf16 v[72:75], v[166:169], v[214:217], v[72:75]
	v_mfma_f32_16x16x32_bf16 v[72:75], v[170:173], v[218:221], v[72:75]
	v_mfma_f32_16x16x32_bf16 v[68:71], v[174:177], v[214:217], v[68:71]
	v_mfma_f32_16x16x32_bf16 v[68:71], v[186:189], v[218:221], v[68:71]
	s_barrier
	s_add_i32 m0, s58, 0x10000
	ds_read_b128 v[190:193], v157 offset:16384
	ds_read_b128 v[194:197], v157 offset:17408
	global_load_lds_dwordx4 v134, s[38:39]
	s_add_i32 m0, s58, 0x12000
	s_add_u32 s98, s38, 0x100000
	s_addc_u32 s99, s39, 0
	ds_read_b128 v[198:201], v157 offset:18432
	global_load_lds_dwordx4 v138, s[38:39]
	s_add_i32 m0, s58, 0x14000
	ds_read_b128 v[202:205], v157 offset:19456
	ds_read_b128 v[206:209], v157 offset:20480
	global_load_lds_dwordx4 v134, s[98:99]
	s_add_i32 m0, s58, 0x16000
	ds_read_b128 v[210:213], v157 offset:21504
	ds_read_b128 v[214:217], v157 offset:22528
	global_load_lds_dwordx4 v138, s[98:99]
	s_mov_b32 m0, s29
	ds_read_b128 v[218:221], v157 offset:23552
	global_load_lds_dwordx4 v132, s[42:43]
	s_mov_b32 m0, s31
	s_nop 0
	global_load_lds_dwordx4 v136, s[42:43]
	s_add_u32 s100, s38, 0x100
	s_addc_u32 s101, s39, 0
	s_cmp_eq_u32 s12, 58
	s_cselect_b32 s100, s36, s100
	s_cselect_b32 s101, s37, s101
	s_bitcmp1_b32 s58, 12
	s_cselect_b32 s100, s100, s38
	s_cselect_b32 s101, s101, s39
	v_lshl_add_u64 v[242:243], s[100:101], 0, v[250:251]
	s_mov_b32 m0, 0x21800
	s_mov_b64 exec, 0xff
	s_nop 0
	global_load_lds_dword v[242:243], off
	s_mov_b64 exec, -1
	s_waitcnt vmcnt(9)
	s_waitcnt lgkmcnt(0)
	s_barrier
	v_mfma_f32_16x16x32_bf16 v[64:67], v[146:149], v[190:193], v[64:67]
	v_mfma_f32_16x16x32_bf16 v[64:67], v[150:153], v[194:197], v[64:67]
	v_mfma_f32_16x16x32_bf16 v[60:63], v[158:161], v[190:193], v[60:63]
	v_mfma_f32_16x16x32_bf16 v[60:63], v[162:165], v[194:197], v[60:63]
	v_mfma_f32_16x16x32_bf16 v[48:51], v[146:149], v[198:201], v[48:51]
	v_mfma_f32_16x16x32_bf16 v[48:51], v[150:153], v[202:205], v[48:51]
	v_mfma_f32_16x16x32_bf16 v[44:47], v[158:161], v[198:201], v[44:47]
	v_mfma_f32_16x16x32_bf16 v[44:47], v[162:165], v[202:205], v[44:47]
	v_mfma_f32_16x16x32_bf16 v[32:35], v[146:149], v[206:209], v[32:35]
	v_mfma_f32_16x16x32_bf16 v[32:35], v[150:153], v[210:213], v[32:35]
	v_mfma_f32_16x16x32_bf16 v[28:31], v[158:161], v[206:209], v[28:31]
	v_mfma_f32_16x16x32_bf16 v[28:31], v[162:165], v[210:213], v[28:31]
	v_mfma_f32_16x16x32_bf16 v[16:19], v[146:149], v[214:217], v[16:19]
	v_mfma_f32_16x16x32_bf16 v[16:19], v[150:153], v[218:221], v[16:19]
	v_mfma_f32_16x16x32_bf16 v[12:15], v[158:161], v[214:217], v[12:15]
	v_mfma_f32_16x16x32_bf16 v[12:15], v[162:165], v[218:221], v[12:15]
	v_mfma_f32_16x16x32_bf16 v[56:59], v[166:169], v[190:193], v[56:59]
	v_mfma_f32_16x16x32_bf16 v[56:59], v[170:173], v[194:197], v[56:59]
	v_mfma_f32_16x16x32_bf16 v[52:55], v[174:177], v[190:193], v[52:55]
	v_mfma_f32_16x16x32_bf16 v[52:55], v[186:189], v[194:197], v[52:55]
	v_mfma_f32_16x16x32_bf16 v[40:43], v[166:169], v[198:201], v[40:43]
	v_mfma_f32_16x16x32_bf16 v[40:43], v[170:173], v[202:205], v[40:43]
	v_mfma_f32_16x16x32_bf16 v[36:39], v[174:177], v[198:201], v[36:39]
	v_mfma_f32_16x16x32_bf16 v[36:39], v[186:189], v[202:205], v[36:39]
	v_mfma_f32_16x16x32_bf16 v[24:27], v[166:169], v[206:209], v[24:27]
	v_mfma_f32_16x16x32_bf16 v[24:27], v[170:173], v[210:213], v[24:27]
	v_mfma_f32_16x16x32_bf16 v[20:23], v[174:177], v[206:209], v[20:23]
	v_mfma_f32_16x16x32_bf16 v[20:23], v[186:189], v[210:213], v[20:23]
	v_mfma_f32_16x16x32_bf16 v[8:11], v[166:169], v[214:217], v[8:11]
	v_mfma_f32_16x16x32_bf16 v[8:11], v[170:173], v[218:221], v[8:11]
	v_mfma_f32_16x16x32_bf16 v[4:7], v[174:177], v[214:217], v[4:7]
	v_mfma_f32_16x16x32_bf16 v[4:7], v[186:189], v[218:221], v[4:7]
	s_barrier
	s_add_u32 s100, s42, 0x100000
	s_addc_u32 s101, s43, 0
	s_mov_b32 m0, s59
	ds_read_b128 v[146:149], v252 offset:32768
	ds_read_b128 v[150:153], v252 offset:33792
	global_load_lds_dwordx4 v132, s[100:101]
	s_mov_b32 m0, s94
	ds_read_b128 v[158:161], v252 offset:34816
	ds_read_b128 v[162:165], v252 offset:35840
	global_load_lds_dwordx4 v136, s[100:101]
	ds_read_b128 v[166:169], v252 offset:49152
	ds_read_b128 v[170:173], v252 offset:50176
	ds_read_b128 v[174:177], v252 offset:51200
	ds_read_b128 v[186:189], v252 offset:52224
	ds_read_b128 v[190:193], v157 offset:32768
	ds_read_b128 v[194:197], v157 offset:33792
	ds_read_b128 v[198:201], v157 offset:34816
	ds_read_b128 v[202:205], v157 offset:35840
	ds_read_b128 v[206:209], v157 offset:36864
	ds_read_b128 v[210:213], v157 offset:37888
	ds_read_b128 v[214:217], v157 offset:38912
	ds_read_b128 v[218:221], v157 offset:39936
	s_waitcnt vmcnt(9)
	s_waitcnt lgkmcnt(0)
	s_barrier
	v_mfma_f32_16x16x32_bf16 v[128:131], v[146:149], v[190:193], v[128:131]
	v_mfma_f32_16x16x32_bf16 v[128:131], v[150:153], v[194:197], v[128:131]
	v_mfma_f32_16x16x32_bf16 v[124:127], v[158:161], v[190:193], v[124:127]
	v_mfma_f32_16x16x32_bf16 v[124:127], v[162:165], v[194:197], v[124:127]
	v_mfma_f32_16x16x32_bf16 v[112:115], v[146:149], v[198:201], v[112:115]
	v_mfma_f32_16x16x32_bf16 v[112:115], v[150:153], v[202:205], v[112:115]
	v_mfma_f32_16x16x32_bf16 v[108:111], v[158:161], v[198:201], v[108:111]
	v_mfma_f32_16x16x32_bf16 v[108:111], v[162:165], v[202:205], v[108:111]
	v_mfma_f32_16x16x32_bf16 v[96:99], v[146:149], v[206:209], v[96:99]
	v_mfma_f32_16x16x32_bf16 v[96:99], v[150:153], v[210:213], v[96:99]
	v_mfma_f32_16x16x32_bf16 v[92:95], v[158:161], v[206:209], v[92:95]
	v_mfma_f32_16x16x32_bf16 v[92:95], v[162:165], v[210:213], v[92:95]
	v_mfma_f32_16x16x32_bf16 v[80:83], v[146:149], v[214:217], v[80:83]
	v_mfma_f32_16x16x32_bf16 v[80:83], v[150:153], v[218:221], v[80:83]
	v_mfma_f32_16x16x32_bf16 v[76:79], v[158:161], v[214:217], v[76:79]
	v_mfma_f32_16x16x32_bf16 v[76:79], v[162:165], v[218:221], v[76:79]
	v_mfma_f32_16x16x32_bf16 v[120:123], v[166:169], v[190:193], v[120:123]
	v_mfma_f32_16x16x32_bf16 v[120:123], v[170:173], v[194:197], v[120:123]
	v_mfma_f32_16x16x32_bf16 v[116:119], v[174:177], v[190:193], v[116:119]
	v_mfma_f32_16x16x32_bf16 v[116:119], v[186:189], v[194:197], v[116:119]
	v_mfma_f32_16x16x32_bf16 v[104:107], v[166:169], v[198:201], v[104:107]
	v_mfma_f32_16x16x32_bf16 v[104:107], v[170:173], v[202:205], v[104:107]
	v_mfma_f32_16x16x32_bf16 v[100:103], v[174:177], v[198:201], v[100:103]
	v_mfma_f32_16x16x32_bf16 v[100:103], v[186:189], v[202:205], v[100:103]
	v_mfma_f32_16x16x32_bf16 v[88:91], v[166:169], v[206:209], v[88:91]
	v_mfma_f32_16x16x32_bf16 v[88:91], v[170:173], v[210:213], v[88:91]
	v_mfma_f32_16x16x32_bf16 v[84:87], v[174:177], v[206:209], v[84:87]
	v_mfma_f32_16x16x32_bf16 v[84:87], v[186:189], v[210:213], v[84:87]
	v_mfma_f32_16x16x32_bf16 v[72:75], v[166:169], v[214:217], v[72:75]
	v_mfma_f32_16x16x32_bf16 v[72:75], v[170:173], v[218:221], v[72:75]
	v_mfma_f32_16x16x32_bf16 v[68:71], v[174:177], v[214:217], v[68:71]
	v_mfma_f32_16x16x32_bf16 v[68:71], v[186:189], v[218:221], v[68:71]
	s_barrier
	s_add_u32 s38, s38, 0x80
	s_addc_u32 s39, s39, 0
	s_add_i32 m0, s58, 0x18000
	ds_read_b128 v[190:193], v157 offset:49152
	ds_read_b128 v[194:197], v157 offset:50176
	global_load_lds_dwordx4 v134, s[38:39]
	s_add_i32 m0, s58, 0x1a000
	s_add_u32 s98, s98, 0x80
	s_addc_u32 s99, s99, 0
	ds_read_b128 v[198:201], v157 offset:51200
	global_load_lds_dwordx4 v138, s[38:39]
	s_add_i32 m0, s58, 0x1c000
	ds_read_b128 v[202:205], v157 offset:52224
	ds_read_b128 v[206:209], v157 offset:53248
	global_load_lds_dwordx4 v134, s[98:99]
	s_add_i32 m0, s58, 0x1e000
	s_add_u32 s42, s42, 0x80
	s_addc_u32 s43, s43, 0
	ds_read_b128 v[210:213], v157 offset:54272
	ds_read_b128 v[214:217], v157 offset:55296
	global_load_lds_dwordx4 v138, s[98:99]
	s_mov_b32 m0, s14
	ds_read_b128 v[218:221], v157 offset:56320
	global_load_lds_dwordx4 v132, s[42:43]
	s_mov_b32 m0, s15
	s_nop 0
	global_load_lds_dwordx4 v136, s[42:43]
	s_waitcnt vmcnt(9)
	s_waitcnt lgkmcnt(0)
	s_barrier
	v_mfma_f32_16x16x32_bf16 v[64:67], v[146:149], v[190:193], v[64:67]
	v_mfma_f32_16x16x32_bf16 v[64:67], v[150:153], v[194:197], v[64:67]
	v_mfma_f32_16x16x32_bf16 v[60:63], v[158:161], v[190:193], v[60:63]
	v_mfma_f32_16x16x32_bf16 v[60:63], v[162:165], v[194:197], v[60:63]
	v_mfma_f32_16x16x32_bf16 v[48:51], v[146:149], v[198:201], v[48:51]
	v_mfma_f32_16x16x32_bf16 v[48:51], v[150:153], v[202:205], v[48:51]
	v_mfma_f32_16x16x32_bf16 v[44:47], v[158:161], v[198:201], v[44:47]
	v_mfma_f32_16x16x32_bf16 v[44:47], v[162:165], v[202:205], v[44:47]
	v_mfma_f32_16x16x32_bf16 v[32:35], v[146:149], v[206:209], v[32:35]
	v_mfma_f32_16x16x32_bf16 v[32:35], v[150:153], v[210:213], v[32:35]
	v_mfma_f32_16x16x32_bf16 v[28:31], v[158:161], v[206:209], v[28:31]
	v_mfma_f32_16x16x32_bf16 v[28:31], v[162:165], v[210:213], v[28:31]
	v_mfma_f32_16x16x32_bf16 v[16:19], v[146:149], v[214:217], v[16:19]
	v_mfma_f32_16x16x32_bf16 v[16:19], v[150:153], v[218:221], v[16:19]
	v_mfma_f32_16x16x32_bf16 v[12:15], v[158:161], v[214:217], v[12:15]
	v_mfma_f32_16x16x32_bf16 v[12:15], v[162:165], v[218:221], v[12:15]
	v_mfma_f32_16x16x32_bf16 v[56:59], v[166:169], v[190:193], v[56:59]
	v_mfma_f32_16x16x32_bf16 v[56:59], v[170:173], v[194:197], v[56:59]
	v_mfma_f32_16x16x32_bf16 v[52:55], v[174:177], v[190:193], v[52:55]
	v_mfma_f32_16x16x32_bf16 v[52:55], v[186:189], v[194:197], v[52:55]
	v_mfma_f32_16x16x32_bf16 v[40:43], v[166:169], v[198:201], v[40:43]
	v_mfma_f32_16x16x32_bf16 v[40:43], v[170:173], v[202:205], v[40:43]
	v_mfma_f32_16x16x32_bf16 v[36:39], v[174:177], v[198:201], v[36:39]
	v_mfma_f32_16x16x32_bf16 v[36:39], v[186:189], v[202:205], v[36:39]
	v_mfma_f32_16x16x32_bf16 v[24:27], v[166:169], v[206:209], v[24:27]
	v_mfma_f32_16x16x32_bf16 v[24:27], v[170:173], v[210:213], v[24:27]
	v_mfma_f32_16x16x32_bf16 v[20:23], v[174:177], v[206:209], v[20:23]
	v_mfma_f32_16x16x32_bf16 v[20:23], v[186:189], v[210:213], v[20:23]
	v_mfma_f32_16x16x32_bf16 v[8:11], v[166:169], v[214:217], v[8:11]
	v_mfma_f32_16x16x32_bf16 v[8:11], v[170:173], v[218:221], v[8:11]
	v_mfma_f32_16x16x32_bf16 v[4:7], v[174:177], v[214:217], v[4:7]
	v_mfma_f32_16x16x32_bf16 v[4:7], v[186:189], v[218:221], v[4:7]
	s_barrier
	s_add_i32 s12, s12, 2
	s_add_u32 s10, s10, 0x100
	s_addc_u32 s11, s11, 0
	s_add_u32 s0, s0, 0x100
	s_addc_u32 s1, s1, 0
	s_cmp_gt_u32 s12, 61
	s_cbranch_scc0 .LBB0_882
	s_and_b64 vcc, exec, s[48:49]
	s_cbranch_vccz .LBB0_885
	s_barrier

.LBB0_1226:
	s_add_u32 s21, s10, 0xfff00080
	s_addc_u32 s22, s11, -1
	s_cmp_eq_u32 s20, 60
	s_cselect_b32 s31, s53, s22
	s_cselect_b32 s30, s52, s21
	s_cselect_b32 s29, s55, s1
	s_cselect_b32 s28, s54, s0
	s_add_i32 m0, s8, 0xc000
	ds_read_b128 v[144:147], v252
	ds_read_b128 v[154:157], v252 offset:1024
	global_load_lds_dwordx4 v140, s[10:11]
	s_add_i32 m0, s8, 0xe000
	ds_read_b128 v[158:161], v252 offset:2048
	ds_read_b128 v[162:165], v252 offset:3072
	global_load_lds_dwordx4 v142, s[10:11]
	ds_read_b128 v[166:169], v252 offset:16384
	ds_read_b128 v[170:173], v252 offset:17408
	ds_read_b128 v[174:177], v252 offset:18432
	ds_read_b128 v[186:189], v252 offset:19456
	ds_read_b128 v[190:193], v153
	ds_read_b128 v[194:197], v153 offset:1024
	ds_read_b128 v[198:201], v153 offset:2048
	ds_read_b128 v[202:205], v153 offset:3072
	ds_read_b128 v[206:209], v153 offset:4096
	ds_read_b128 v[210:213], v153 offset:5120
	ds_read_b128 v[214:217], v153 offset:6144
	ds_read_b128 v[218:221], v153 offset:7168
	s_waitcnt vmcnt(8)
	s_waitcnt lgkmcnt(0)
	s_barrier
	v_mfma_f32_16x16x32_bf16 v[128:131], v[144:147], v[190:193], v[128:131]
	v_mfma_f32_16x16x32_bf16 v[128:131], v[154:157], v[194:197], v[128:131]
	v_mfma_f32_16x16x32_bf16 v[124:127], v[158:161], v[190:193], v[124:127]
	v_mfma_f32_16x16x32_bf16 v[124:127], v[162:165], v[194:197], v[124:127]
	v_mfma_f32_16x16x32_bf16 v[112:115], v[144:147], v[198:201], v[112:115]
	v_mfma_f32_16x16x32_bf16 v[112:115], v[154:157], v[202:205], v[112:115]
	v_mfma_f32_16x16x32_bf16 v[108:111], v[158:161], v[198:201], v[108:111]
	v_mfma_f32_16x16x32_bf16 v[108:111], v[162:165], v[202:205], v[108:111]
	v_mfma_f32_16x16x32_bf16 v[96:99], v[144:147], v[206:209], v[96:99]
	v_mfma_f32_16x16x32_bf16 v[96:99], v[154:157], v[210:213], v[96:99]
	v_mfma_f32_16x16x32_bf16 v[92:95], v[158:161], v[206:209], v[92:95]
	v_mfma_f32_16x16x32_bf16 v[92:95], v[162:165], v[210:213], v[92:95]
	v_mfma_f32_16x16x32_bf16 v[80:83], v[144:147], v[214:217], v[80:83]
	v_mfma_f32_16x16x32_bf16 v[80:83], v[154:157], v[218:221], v[80:83]
	v_mfma_f32_16x16x32_bf16 v[76:79], v[158:161], v[214:217], v[76:79]
	v_mfma_f32_16x16x32_bf16 v[76:79], v[162:165], v[218:221], v[76:79]
	v_mfma_f32_16x16x32_bf16 v[120:123], v[166:169], v[190:193], v[120:123]
	v_mfma_f32_16x16x32_bf16 v[120:123], v[170:173], v[194:197], v[120:123]
	v_mfma_f32_16x16x32_bf16 v[116:119], v[174:177], v[190:193], v[116:119]
	v_mfma_f32_16x16x32_bf16 v[116:119], v[186:189], v[194:197], v[116:119]
	v_mfma_f32_16x16x32_bf16 v[104:107], v[166:169], v[198:201], v[104:107]
	v_mfma_f32_16x16x32_bf16 v[104:107], v[170:173], v[202:205], v[104:107]
	v_mfma_f32_16x16x32_bf16 v[100:103], v[174:177], v[198:201], v[100:103]
	v_mfma_f32_16x16x32_bf16 v[100:103], v[186:189], v[202:205], v[100:103]
	v_mfma_f32_16x16x32_bf16 v[88:91], v[166:169], v[206:209], v[88:91]
	v_mfma_f32_16x16x32_bf16 v[88:91], v[170:173], v[210:213], v[88:91]
	v_mfma_f32_16x16x32_bf16 v[84:87], v[174:177], v[206:209], v[84:87]
	v_mfma_f32_16x16x32_bf16 v[84:87], v[186:189], v[210:213], v[84:87]
	v_mfma_f32_16x16x32_bf16 v[72:75], v[166:169], v[214:217], v[72:75]
	v_mfma_f32_16x16x32_bf16 v[72:75], v[170:173], v[218:221], v[72:75]
	v_mfma_f32_16x16x32_bf16 v[68:71], v[174:177], v[214:217], v[68:71]
	v_mfma_f32_16x16x32_bf16 v[68:71], v[186:189], v[218:221], v[68:71]
	s_barrier
	s_add_i32 m0, s38, 0x10000
	ds_read_b128 v[190:193], v153 offset:16384
	ds_read_b128 v[194:197], v153 offset:17408
	global_load_lds_dwordx4 v136, s[28:29]
	s_add_i32 m0, s38, 0x12000
	s_add_u32 s98, s28, 0x100000
	s_addc_u32 s99, s29, 0
	ds_read_b128 v[198:201], v153 offset:18432
	global_load_lds_dwordx4 v132, s[28:29]
	s_add_i32 m0, s38, 0x14000
	ds_read_b128 v[202:205], v153 offset:19456
	ds_read_b128 v[206:209], v153 offset:20480
	global_load_lds_dwordx4 v136, s[98:99]
	s_add_i32 m0, s38, 0x16000
	ds_read_b128 v[210:213], v153 offset:21504
	ds_read_b128 v[214:217], v153 offset:22528
	global_load_lds_dwordx4 v132, s[98:99]
	s_mov_b32 m0, s8
	ds_read_b128 v[218:221], v153 offset:23552
	global_load_lds_dwordx4 v138, s[30:31]
	s_mov_b32 m0, s9
	s_nop 0
	global_load_lds_dwordx4 v134, s[30:31]
	s_add_u32 s100, s28, 0x100
	s_addc_u32 s101, s29, 0
	s_cmp_eq_u32 s20, 58
	s_cselect_b32 s100, s54, s100
	s_cselect_b32 s101, s55, s101
	s_bitcmp1_b32 s38, 12
	s_cselect_b32 s100, s100, s28
	s_cselect_b32 s101, s101, s29
	v_lshl_add_u64 v[242:243], s[100:101], 0, v[250:251]
	s_mov_b32 m0, 0x21800
	s_mov_b64 exec, 0xff
	s_nop 0
	global_load_lds_dword v[242:243], off
	s_mov_b64 exec, -1
	s_waitcnt vmcnt(9)
	s_waitcnt lgkmcnt(0)
	s_barrier
	v_mfma_f32_16x16x32_bf16 v[64:67], v[144:147], v[190:193], v[64:67]
	v_mfma_f32_16x16x32_bf16 v[64:67], v[154:157], v[194:197], v[64:67]
	v_mfma_f32_16x16x32_bf16 v[60:63], v[158:161], v[190:193], v[60:63]
	v_mfma_f32_16x16x32_bf16 v[60:63], v[162:165], v[194:197], v[60:63]
	v_mfma_f32_16x16x32_bf16 v[48:51], v[144:147], v[198:201], v[48:51]
	v_mfma_f32_16x16x32_bf16 v[48:51], v[154:157], v[202:205], v[48:51]
	v_mfma_f32_16x16x32_bf16 v[44:47], v[158:161], v[198:201], v[44:47]
	v_mfma_f32_16x16x32_bf16 v[44:47], v[162:165], v[202:205], v[44:47]
	v_mfma_f32_16x16x32_bf16 v[32:35], v[144:147], v[206:209], v[32:35]
	v_mfma_f32_16x16x32_bf16 v[32:35], v[154:157], v[210:213], v[32:35]
	v_mfma_f32_16x16x32_bf16 v[28:31], v[158:161], v[206:209], v[28:31]
	v_mfma_f32_16x16x32_bf16 v[28:31], v[162:165], v[210:213], v[28:31]
	v_mfma_f32_16x16x32_bf16 v[16:19], v[144:147], v[214:217], v[16:19]
	v_mfma_f32_16x16x32_bf16 v[16:19], v[154:157], v[218:221], v[16:19]
	v_mfma_f32_16x16x32_bf16 v[12:15], v[158:161], v[214:217], v[12:15]
	v_mfma_f32_16x16x32_bf16 v[12:15], v[162:165], v[218:221], v[12:15]
	v_mfma_f32_16x16x32_bf16 v[56:59], v[166:169], v[190:193], v[56:59]
	v_mfma_f32_16x16x32_bf16 v[56:59], v[170:173], v[194:197], v[56:59]
	v_mfma_f32_16x16x32_bf16 v[52:55], v[174:177], v[190:193], v[52:55]
	v_mfma_f32_16x16x32_bf16 v[52:55], v[186:189], v[194:197], v[52:55]
	v_mfma_f32_16x16x32_bf16 v[40:43], v[166:169], v[198:201], v[40:43]
	v_mfma_f32_16x16x32_bf16 v[40:43], v[170:173], v[202:205], v[40:43]
	v_mfma_f32_16x16x32_bf16 v[36:39], v[174:177], v[198:201], v[36:39]
	v_mfma_f32_16x16x32_bf16 v[36:39], v[186:189], v[202:205], v[36:39]
	v_mfma_f32_16x16x32_bf16 v[24:27], v[166:169], v[206:209], v[24:27]
	v_mfma_f32_16x16x32_bf16 v[24:27], v[170:173], v[210:213], v[24:27]
	v_mfma_f32_16x16x32_bf16 v[20:23], v[174:177], v[206:209], v[20:23]
	v_mfma_f32_16x16x32_bf16 v[20:23], v[186:189], v[210:213], v[20:23]
	v_mfma_f32_16x16x32_bf16 v[8:11], v[166:169], v[214:217], v[8:11]
	v_mfma_f32_16x16x32_bf16 v[8:11], v[170:173], v[218:221], v[8:11]
	v_mfma_f32_16x16x32_bf16 v[4:7], v[174:177], v[214:217], v[4:7]
	v_mfma_f32_16x16x32_bf16 v[4:7], v[186:189], v[218:221], v[4:7]
	s_barrier
	s_add_u32 s100, s30, 0x100000
	s_addc_u32 s101, s31, 0
	s_mov_b32 m0, s16
	ds_read_b128 v[144:147], v252 offset:32768
	ds_read_b128 v[154:157], v252 offset:33792
	global_load_lds_dwordx4 v138, s[100:101]
	s_mov_b32 m0, s17
	ds_read_b128 v[158:161], v252 offset:34816
	ds_read_b128 v[162:165], v252 offset:35840
	global_load_lds_dwordx4 v134, s[100:101]
	ds_read_b128 v[166:169], v252 offset:49152
	ds_read_b128 v[170:173], v252 offset:50176
	ds_read_b128 v[174:177], v252 offset:51200
	ds_read_b128 v[186:189], v252 offset:52224
	ds_read_b128 v[190:193], v153 offset:32768
	ds_read_b128 v[194:197], v153 offset:33792
	ds_read_b128 v[198:201], v153 offset:34816
	ds_read_b128 v[202:205], v153 offset:35840
	ds_read_b128 v[206:209], v153 offset:36864
	ds_read_b128 v[210:213], v153 offset:37888
	ds_read_b128 v[214:217], v153 offset:38912
	ds_read_b128 v[218:221], v153 offset:39936
	s_waitcnt vmcnt(9)
	s_waitcnt lgkmcnt(0)
	s_barrier
	v_mfma_f32_16x16x32_bf16 v[128:131], v[144:147], v[190:193], v[128:131]
	v_mfma_f32_16x16x32_bf16 v[128:131], v[154:157], v[194:197], v[128:131]
	v_mfma_f32_16x16x32_bf16 v[124:127], v[158:161], v[190:193], v[124:127]
	v_mfma_f32_16x16x32_bf16 v[124:127], v[162:165], v[194:197], v[124:127]
	v_mfma_f32_16x16x32_bf16 v[112:115], v[144:147], v[198:201], v[112:115]
	v_mfma_f32_16x16x32_bf16 v[112:115], v[154:157], v[202:205], v[112:115]
	v_mfma_f32_16x16x32_bf16 v[108:111], v[158:161], v[198:201], v[108:111]
	v_mfma_f32_16x16x32_bf16 v[108:111], v[162:165], v[202:205], v[108:111]
	v_mfma_f32_16x16x32_bf16 v[96:99], v[144:147], v[206:209], v[96:99]
	v_mfma_f32_16x16x32_bf16 v[96:99], v[154:157], v[210:213], v[96:99]
	v_mfma_f32_16x16x32_bf16 v[92:95], v[158:161], v[206:209], v[92:95]
	v_mfma_f32_16x16x32_bf16 v[92:95], v[162:165], v[210:213], v[92:95]
	v_mfma_f32_16x16x32_bf16 v[80:83], v[144:147], v[214:217], v[80:83]
	v_mfma_f32_16x16x32_bf16 v[80:83], v[154:157], v[218:221], v[80:83]
	v_mfma_f32_16x16x32_bf16 v[76:79], v[158:161], v[214:217], v[76:79]
	v_mfma_f32_16x16x32_bf16 v[76:79], v[162:165], v[218:221], v[76:79]
	v_mfma_f32_16x16x32_bf16 v[120:123], v[166:169], v[190:193], v[120:123]
	v_mfma_f32_16x16x32_bf16 v[120:123], v[170:173], v[194:197], v[120:123]
	v_mfma_f32_16x16x32_bf16 v[116:119], v[174:177], v[190:193], v[116:119]
	v_mfma_f32_16x16x32_bf16 v[116:119], v[186:189], v[194:197], v[116:119]
	v_mfma_f32_16x16x32_bf16 v[104:107], v[166:169], v[198:201], v[104:107]
	v_mfma_f32_16x16x32_bf16 v[104:107], v[170:173], v[202:205], v[104:107]
	v_mfma_f32_16x16x32_bf16 v[100:103], v[174:177], v[198:201], v[100:103]
	v_mfma_f32_16x16x32_bf16 v[100:103], v[186:189], v[202:205], v[100:103]
	v_mfma_f32_16x16x32_bf16 v[88:91], v[166:169], v[206:209], v[88:91]
	v_mfma_f32_16x16x32_bf16 v[88:91], v[170:173], v[210:213], v[88:91]
	v_mfma_f32_16x16x32_bf16 v[84:87], v[174:177], v[206:209], v[84:87]
	v_mfma_f32_16x16x32_bf16 v[84:87], v[186:189], v[210:213], v[84:87]
	v_mfma_f32_16x16x32_bf16 v[72:75], v[166:169], v[214:217], v[72:75]
	v_mfma_f32_16x16x32_bf16 v[72:75], v[170:173], v[218:221], v[72:75]
	v_mfma_f32_16x16x32_bf16 v[68:71], v[174:177], v[214:217], v[68:71]
	v_mfma_f32_16x16x32_bf16 v[68:71], v[186:189], v[218:221], v[68:71]
	s_barrier
	s_add_u32 s28, s28, 0x80
	s_addc_u32 s29, s29, 0
	s_add_i32 m0, s38, 0x18000
	ds_read_b128 v[190:193], v153 offset:49152
	ds_read_b128 v[194:197], v153 offset:50176
	global_load_lds_dwordx4 v136, s[28:29]
	s_add_i32 m0, s38, 0x1a000
	s_add_u32 s98, s98, 0x80
	s_addc_u32 s99, s99, 0
	ds_read_b128 v[198:201], v153 offset:51200
	global_load_lds_dwordx4 v132, s[28:29]
	s_add_i32 m0, s38, 0x1c000
	ds_read_b128 v[202:205], v153 offset:52224
	ds_read_b128 v[206:209], v153 offset:53248
	global_load_lds_dwordx4 v136, s[98:99]
	s_add_i32 m0, s38, 0x1e000
	s_add_u32 s30, s30, 0x80
	s_addc_u32 s31, s31, 0
	ds_read_b128 v[210:213], v153 offset:54272
	ds_read_b128 v[214:217], v153 offset:55296
	global_load_lds_dwordx4 v132, s[98:99]
	s_mov_b32 m0, s45
	ds_read_b128 v[218:221], v153 offset:56320
	global_load_lds_dwordx4 v138, s[30:31]
	s_mov_b32 m0, s46
	s_nop 0
	global_load_lds_dwordx4 v134, s[30:31]
	s_waitcnt vmcnt(9)
	s_waitcnt lgkmcnt(0)
	s_barrier
	v_mfma_f32_16x16x32_bf16 v[64:67], v[144:147], v[190:193], v[64:67]
	v_mfma_f32_16x16x32_bf16 v[64:67], v[154:157], v[194:197], v[64:67]
	v_mfma_f32_16x16x32_bf16 v[60:63], v[158:161], v[190:193], v[60:63]
	v_mfma_f32_16x16x32_bf16 v[60:63], v[162:165], v[194:197], v[60:63]
	v_mfma_f32_16x16x32_bf16 v[48:51], v[144:147], v[198:201], v[48:51]
	v_mfma_f32_16x16x32_bf16 v[48:51], v[154:157], v[202:205], v[48:51]
	v_mfma_f32_16x16x32_bf16 v[44:47], v[158:161], v[198:201], v[44:47]
	v_mfma_f32_16x16x32_bf16 v[44:47], v[162:165], v[202:205], v[44:47]
	v_mfma_f32_16x16x32_bf16 v[32:35], v[144:147], v[206:209], v[32:35]
	v_mfma_f32_16x16x32_bf16 v[32:35], v[154:157], v[210:213], v[32:35]
	v_mfma_f32_16x16x32_bf16 v[28:31], v[158:161], v[206:209], v[28:31]
	v_mfma_f32_16x16x32_bf16 v[28:31], v[162:165], v[210:213], v[28:31]
	v_mfma_f32_16x16x32_bf16 v[16:19], v[144:147], v[214:217], v[16:19]
	v_mfma_f32_16x16x32_bf16 v[16:19], v[154:157], v[218:221], v[16:19]
	v_mfma_f32_16x16x32_bf16 v[12:15], v[158:161], v[214:217], v[12:15]
	v_mfma_f32_16x16x32_bf16 v[12:15], v[162:165], v[218:221], v[12:15]
	v_mfma_f32_16x16x32_bf16 v[56:59], v[166:169], v[190:193], v[56:59]
	v_mfma_f32_16x16x32_bf16 v[56:59], v[170:173], v[194:197], v[56:59]
	v_mfma_f32_16x16x32_bf16 v[52:55], v[174:177], v[190:193], v[52:55]
	v_mfma_f32_16x16x32_bf16 v[52:55], v[186:189], v[194:197], v[52:55]
	v_mfma_f32_16x16x32_bf16 v[40:43], v[166:169], v[198:201], v[40:43]
	v_mfma_f32_16x16x32_bf16 v[40:43], v[170:173], v[202:205], v[40:43]
	v_mfma_f32_16x16x32_bf16 v[36:39], v[174:177], v[198:201], v[36:39]
	v_mfma_f32_16x16x32_bf16 v[36:39], v[186:189], v[202:205], v[36:39]
	v_mfma_f32_16x16x32_bf16 v[24:27], v[166:169], v[206:209], v[24:27]
	v_mfma_f32_16x16x32_bf16 v[24:27], v[170:173], v[210:213], v[24:27]
	v_mfma_f32_16x16x32_bf16 v[20:23], v[174:177], v[206:209], v[20:23]
	v_mfma_f32_16x16x32_bf16 v[20:23], v[186:189], v[210:213], v[20:23]
	v_mfma_f32_16x16x32_bf16 v[8:11], v[166:169], v[214:217], v[8:11]
	v_mfma_f32_16x16x32_bf16 v[8:11], v[170:173], v[218:221], v[8:11]
	v_mfma_f32_16x16x32_bf16 v[4:7], v[174:177], v[214:217], v[4:7]
	v_mfma_f32_16x16x32_bf16 v[4:7], v[186:189], v[218:221], v[4:7]
	s_barrier
	s_add_i32 s20, s20, 2
	s_add_u32 s10, s10, 0x100
	s_addc_u32 s11, s11, 0
	s_add_u32 s0, s0, 0x100
	s_addc_u32 s1, s1, 0
	s_cmp_gt_u32 s20, 61
	s_cbranch_scc0 .LBB0_1226
	s_and_b64 vcc, exec, s[48:49]
	s_cbranch_vccz .LBB0_1229
	s_barrier
